# G1 epilogue: non-q tiles (scale exactly 1.0) take a copy of the store code without the 64 multiplies, bf16 conversion reads the accumulators directly; stacked on stack34
# baseline (speedup 1.0000x reference)
; __device__ __forceinline__ unsigned cvt_pk_bf16(float lo, float hi) { unsigned r; asm volatile("v_cvt_pk_bf16_f32 %0, %1, %2" : "=v"(r) : "v"(lo), "v"(hi)); return r; }
; #define x (arg_in(0))
;     __device__ __forceinline__ void operator()(const f32x4 (&acc)[2][2][4][2], const Unit& u, int wr, int wc, int fr, int fq) const {
;         const int row0 = u.pm * BM + wr * 64 + fr, col0 = u.pn * BM + wc * 32 + 8 * fq;
;         const float sc = u.pn < 2 ? qscale : 1.f;
; #pragma unroll
;         for (int ai = 0; ai < 2; ++ai)
; #pragma unroll
;             for (int m = 0; m < 4; ++m) { bf16_t* rowp = O + (size_t)(u.pm >> 4) * bpad + (size_t)(row0 + ai * HALF + m * 16) * ldc + col0;
; #pragma unroll
;                 for (int bj = 0; bj < 2; ++bj) { const f32x4 v0 = acc[ai][bj][m][0] * sc, v1 = acc[ai][bj][m][1] * sc;
;                     u32x4 w; w.x = cvt_pk_bf16(v0[0], v0[1]); w.y = cvt_pk_bf16(v0[2], v0[3]); w.z = cvt_pk_bf16(v1[0], v1[1]); w.w = cvt_pk_bf16(v1[2], v1[3]);
;                     *(u32x4*)(rowp + bj * HALF) = w; } }
.LBB0_167:
	s_cmp_lt_i32 s70, 2
	s_cselect_b64 vcc, -1, 0
	s_ashr_i32 s36, s88, 4
	s_ashr_i32 s37, s36, 31
	s_lshl_b64 s[36:37], s[36:37], 21
	s_add_u32 s36, s23, s36
	s_addc_u32 s37, s25, s37
	s_mul_i32 s98, s88, 0x140000
	s_lshl_b32 s99, s70, 9
	s_add_u32 s98, s98, s99
	s_add_u32 s98, s36, s98
	s_addc_u32 s99, s37, 0
	v_mul_u32_u24_e32 v149, 0x1400, v141
	v_lshl_add_u32 v149, v147, 1, v149
	s_cmp_lt_i32 s70, 2
	s_cbranch_scc1 .Lg1_qpath
	v_cvt_pk_bf16_f32 v150, v124, v125
	v_cvt_pk_bf16_f32 v151, v126, v127
	v_cvt_pk_bf16_f32 v152, v120, v121
	v_cvt_pk_bf16_f32 v153, v122, v123
	global_store_dwordx4 v149, v[150:153], s[98:99]
	s_nop 1
	v_cvt_pk_bf16_f32 v150, v92, v93
	v_cvt_pk_bf16_f32 v151, v94, v95
	v_cvt_pk_bf16_f32 v152, v88, v89
	v_cvt_pk_bf16_f32 v153, v90, v91
	global_store_dwordx4 v149, v[150:153], s[98:99] offset:256
	s_add_u32 s98, s98, 0x14000
	s_addc_u32 s99, s99, 0
	v_cvt_pk_bf16_f32 v150, v116, v117
	v_cvt_pk_bf16_f32 v151, v118, v119
	v_cvt_pk_bf16_f32 v152, v112, v113
	v_cvt_pk_bf16_f32 v153, v114, v115
	global_store_dwordx4 v149, v[150:153], s[98:99]
	s_nop 1
	v_cvt_pk_bf16_f32 v150, v84, v85
	v_cvt_pk_bf16_f32 v151, v86, v87
	v_cvt_pk_bf16_f32 v152, v80, v81
	v_cvt_pk_bf16_f32 v153, v82, v83
	global_store_dwordx4 v149, v[150:153], s[98:99] offset:256
	s_add_u32 s98, s98, 0x14000
	s_addc_u32 s99, s99, 0
	v_cvt_pk_bf16_f32 v150, v108, v109
	v_cvt_pk_bf16_f32 v151, v110, v111
	v_cvt_pk_bf16_f32 v152, v104, v105
	v_cvt_pk_bf16_f32 v153, v106, v107
	global_store_dwordx4 v149, v[150:153], s[98:99]
	s_nop 1
	v_cvt_pk_bf16_f32 v150, v76, v77
	v_cvt_pk_bf16_f32 v151, v78, v79
	v_cvt_pk_bf16_f32 v152, v72, v73
	v_cvt_pk_bf16_f32 v153, v74, v75
	global_store_dwordx4 v149, v[150:153], s[98:99] offset:256
	s_add_u32 s98, s98, 0x14000
	s_addc_u32 s99, s99, 0
	v_cvt_pk_bf16_f32 v150, v100, v101
	v_cvt_pk_bf16_f32 v151, v102, v103
	v_cvt_pk_bf16_f32 v152, v96, v97
	v_cvt_pk_bf16_f32 v153, v98, v99
	global_store_dwordx4 v149, v[150:153], s[98:99]
	s_nop 1
	v_cvt_pk_bf16_f32 v150, v68, v69
	v_cvt_pk_bf16_f32 v151, v70, v71
	v_cvt_pk_bf16_f32 v152, v64, v65
	v_cvt_pk_bf16_f32 v153, v66, v67
	global_store_dwordx4 v149, v[150:153], s[98:99] offset:256
	s_add_u32 s98, s98, 0x64000
	s_addc_u32 s99, s99, 0
	v_cvt_pk_bf16_f32 v150, v60, v61
	v_cvt_pk_bf16_f32 v151, v62, v63
	v_cvt_pk_bf16_f32 v152, v56, v57
	v_cvt_pk_bf16_f32 v153, v58, v59
	global_store_dwordx4 v149, v[150:153], s[98:99]
	s_nop 1
	v_cvt_pk_bf16_f32 v150, v28, v29
	v_cvt_pk_bf16_f32 v151, v30, v31
	v_cvt_pk_bf16_f32 v152, v24, v25
	v_cvt_pk_bf16_f32 v153, v26, v27
	global_store_dwordx4 v149, v[150:153], s[98:99] offset:256
	s_add_u32 s98, s98, 0x14000
	s_addc_u32 s99, s99, 0
	v_cvt_pk_bf16_f32 v150, v52, v53
	v_cvt_pk_bf16_f32 v151, v54, v55
	v_cvt_pk_bf16_f32 v152, v48, v49
	v_cvt_pk_bf16_f32 v153, v50, v51
	global_store_dwordx4 v149, v[150:153], s[98:99]
	s_nop 1
	v_cvt_pk_bf16_f32 v150, v20, v21
	v_cvt_pk_bf16_f32 v151, v22, v23
	v_cvt_pk_bf16_f32 v152, v16, v17
	v_cvt_pk_bf16_f32 v153, v18, v19
	global_store_dwordx4 v149, v[150:153], s[98:99] offset:256
	s_add_u32 s98, s98, 0x14000
	s_addc_u32 s99, s99, 0
	v_cvt_pk_bf16_f32 v150, v44, v45
	v_cvt_pk_bf16_f32 v151, v46, v47
	v_cvt_pk_bf16_f32 v152, v40, v41
	v_cvt_pk_bf16_f32 v153, v42, v43
	global_store_dwordx4 v149, v[150:153], s[98:99]
	s_nop 1
	v_cvt_pk_bf16_f32 v150, v12, v13
	v_cvt_pk_bf16_f32 v151, v14, v15
	v_cvt_pk_bf16_f32 v152, v8, v9
	v_cvt_pk_bf16_f32 v153, v10, v11
	global_store_dwordx4 v149, v[150:153], s[98:99] offset:256
	s_add_u32 s98, s98, 0x14000
	s_addc_u32 s99, s99, 0
	s_and_b32 s36, s70, -2
	v_cvt_pk_bf16_f32 v142, v36, v37
	v_cvt_pk_bf16_f32 v143, v38, v39
	v_cvt_pk_bf16_f32 v144, v32, v33
	v_cvt_pk_bf16_f32 v145, v34, v35
	global_store_dwordx4 v149, v[142:145], s[98:99]
	s_cmp_lg_u32 s36, 2
	s_movk_i32 s84, 0x3000
	s_mov_b32 s92, 0x358637bd
	v_cvt_pk_bf16_f32 v142, v4, v5
	v_cvt_pk_bf16_f32 v143, v6, v7
	v_cvt_pk_bf16_f32 v144, v0, v1
	v_cvt_pk_bf16_f32 v145, v2, v3
	global_store_dwordx4 v149, v[142:145], s[98:99] offset:256
	s_cbranch_scc1 .LBB0_189
	s_branch .Lg1_join
.Lg1_qpath:
	v_mov_b32_e32 v140, 0x3e8293ee
	v_cndmask_b32_e32 v140, 1.0, v140, vcc
	v_pk_mul_f32 v[150:151], v[140:141], v[124:125] op_sel_hi:[0,1]
	v_pk_mul_f32 v[152:153], v[140:141], v[126:127] op_sel_hi:[0,1]
	v_cvt_pk_bf16_f32 v150, v150, v151
	v_cvt_pk_bf16_f32 v151, v152, v153
	v_pk_mul_f32 v[156:157], v[140:141], v[122:123] op_sel_hi:[0,1]
	v_pk_mul_f32 v[158:159], v[140:141], v[120:121] op_sel_hi:[0,1]
	v_cvt_pk_bf16_f32 v152, v158, v159
	v_cvt_pk_bf16_f32 v153, v156, v157
	global_store_dwordx4 v149, v[150:153], s[98:99]
	v_pk_mul_f32 v[156:157], v[140:141], v[90:91] op_sel_hi:[0,1]
	v_pk_mul_f32 v[158:159], v[140:141], v[88:89] op_sel_hi:[0,1]
	v_pk_mul_f32 v[150:151], v[140:141], v[92:93] op_sel_hi:[0,1]
	v_pk_mul_f32 v[152:153], v[140:141], v[94:95] op_sel_hi:[0,1]
	v_cvt_pk_bf16_f32 v150, v150, v151
	v_cvt_pk_bf16_f32 v151, v152, v153
	v_cvt_pk_bf16_f32 v152, v158, v159
	v_cvt_pk_bf16_f32 v153, v156, v157
	global_store_dwordx4 v149, v[150:153], s[98:99] offset:256
	s_add_u32 s98, s98, 0x14000
	s_addc_u32 s99, s99, 0
	v_pk_mul_f32 v[156:157], v[140:141], v[114:115] op_sel_hi:[0,1]
	v_pk_mul_f32 v[158:159], v[140:141], v[112:113] op_sel_hi:[0,1]
	v_pk_mul_f32 v[150:151], v[140:141], v[116:117] op_sel_hi:[0,1]
	v_pk_mul_f32 v[152:153], v[140:141], v[118:119] op_sel_hi:[0,1]
	v_cvt_pk_bf16_f32 v150, v150, v151
	v_cvt_pk_bf16_f32 v151, v152, v153
	v_cvt_pk_bf16_f32 v152, v158, v159
	v_cvt_pk_bf16_f32 v153, v156, v157
	global_store_dwordx4 v149, v[150:153], s[98:99]
	v_pk_mul_f32 v[156:157], v[140:141], v[82:83] op_sel_hi:[0,1]
; __device__ __forceinline__ unsigned cvt_pk_bf16(float lo, float hi) { unsigned r; asm volatile("v_cvt_pk_bf16_f32 %0, %1, %2" : "=v"(r) : "v"(lo), "v"(hi)); return r; }
; #define x (arg_in(0))
;     __device__ __forceinline__ void operator()(const f32x4 (&acc)[2][2][4][2], const Unit& u, int wr, int wc, int fr, int fq) const {
;     ...
;             for (int m = 0; m < 4; ++m) { bf16_t* rowp = O + (size_t)(u.pm >> 4) * bpad + (size_t)(row0 + ai * HALF + m * 16) * ldc + col0;
; #pragma unroll
;                 for (int bj = 0; bj < 2; ++bj) { const f32x4 v0 = acc[ai][bj][m][0] * sc, v1 = acc[ai][bj][m][1] * sc;
;                     u32x4 w; w.x = cvt_pk_bf16(v0[0], v0[1]); w.y = cvt_pk_bf16(v0[2], v0[3]); w.z = cvt_pk_bf16(v1[0], v1[1]); w.w = cvt_pk_bf16(v1[2], v1[3]);
;                     *(u32x4*)(rowp + bj * HALF) = w; } }
	v_pk_mul_f32 v[158:159], v[140:141], v[80:81] op_sel_hi:[0,1]
	v_pk_mul_f32 v[150:151], v[140:141], v[84:85] op_sel_hi:[0,1]
	v_pk_mul_f32 v[152:153], v[140:141], v[86:87] op_sel_hi:[0,1]
	v_cvt_pk_bf16_f32 v150, v150, v151
	v_cvt_pk_bf16_f32 v151, v152, v153
	v_cvt_pk_bf16_f32 v152, v158, v159
	v_cvt_pk_bf16_f32 v153, v156, v157
	global_store_dwordx4 v149, v[150:153], s[98:99] offset:256
	s_add_u32 s98, s98, 0x14000
	s_addc_u32 s99, s99, 0
	v_pk_mul_f32 v[156:157], v[140:141], v[106:107] op_sel_hi:[0,1]
	v_pk_mul_f32 v[158:159], v[140:141], v[104:105] op_sel_hi:[0,1]
	v_pk_mul_f32 v[150:151], v[140:141], v[108:109] op_sel_hi:[0,1]
	v_pk_mul_f32 v[152:153], v[140:141], v[110:111] op_sel_hi:[0,1]
	v_cvt_pk_bf16_f32 v150, v150, v151
	v_cvt_pk_bf16_f32 v151, v152, v153
	v_cvt_pk_bf16_f32 v152, v158, v159
	v_cvt_pk_bf16_f32 v153, v156, v157
	global_store_dwordx4 v149, v[150:153], s[98:99]
	v_pk_mul_f32 v[156:157], v[140:141], v[74:75] op_sel_hi:[0,1]
	v_pk_mul_f32 v[158:159], v[140:141], v[72:73] op_sel_hi:[0,1]
	v_pk_mul_f32 v[150:151], v[140:141], v[76:77] op_sel_hi:[0,1]
	v_pk_mul_f32 v[152:153], v[140:141], v[78:79] op_sel_hi:[0,1]
	v_cvt_pk_bf16_f32 v150, v150, v151
	v_cvt_pk_bf16_f32 v151, v152, v153
	v_cvt_pk_bf16_f32 v152, v158, v159
	v_cvt_pk_bf16_f32 v153, v156, v157
	global_store_dwordx4 v149, v[150:153], s[98:99] offset:256
	s_add_u32 s98, s98, 0x14000
	s_addc_u32 s99, s99, 0
	v_pk_mul_f32 v[156:157], v[140:141], v[98:99] op_sel_hi:[0,1]
	v_pk_mul_f32 v[158:159], v[140:141], v[96:97] op_sel_hi:[0,1]
	v_pk_mul_f32 v[150:151], v[140:141], v[100:101] op_sel_hi:[0,1]
	v_pk_mul_f32 v[152:153], v[140:141], v[102:103] op_sel_hi:[0,1]
	v_cvt_pk_bf16_f32 v150, v150, v151
	v_cvt_pk_bf16_f32 v151, v152, v153
	v_cvt_pk_bf16_f32 v152, v158, v159
	v_cvt_pk_bf16_f32 v153, v156, v157
	global_store_dwordx4 v149, v[150:153], s[98:99]
	v_pk_mul_f32 v[156:157], v[140:141], v[66:67] op_sel_hi:[0,1]
	v_pk_mul_f32 v[158:159], v[140:141], v[64:65] op_sel_hi:[0,1]
	v_pk_mul_f32 v[150:151], v[140:141], v[68:69] op_sel_hi:[0,1]
	v_pk_mul_f32 v[152:153], v[140:141], v[70:71] op_sel_hi:[0,1]
	v_cvt_pk_bf16_f32 v150, v150, v151
	v_cvt_pk_bf16_f32 v151, v152, v153
	v_cvt_pk_bf16_f32 v152, v158, v159
	v_cvt_pk_bf16_f32 v153, v156, v157
	global_store_dwordx4 v149, v[150:153], s[98:99] offset:256
	s_add_u32 s98, s98, 0x64000
	s_addc_u32 s99, s99, 0
	v_pk_mul_f32 v[156:157], v[140:141], v[58:59] op_sel_hi:[0,1]
	v_pk_mul_f32 v[158:159], v[140:141], v[56:57] op_sel_hi:[0,1]
	v_pk_mul_f32 v[150:151], v[140:141], v[60:61] op_sel_hi:[0,1]
	v_pk_mul_f32 v[152:153], v[140:141], v[62:63] op_sel_hi:[0,1]
	v_cvt_pk_bf16_f32 v150, v150, v151
	v_cvt_pk_bf16_f32 v151, v152, v153
	v_cvt_pk_bf16_f32 v152, v158, v159
	v_cvt_pk_bf16_f32 v153, v156, v157
	global_store_dwordx4 v149, v[150:153], s[98:99]
	v_pk_mul_f32 v[156:157], v[140:141], v[26:27] op_sel_hi:[0,1]
	v_pk_mul_f32 v[158:159], v[140:141], v[24:25] op_sel_hi:[0,1]
	v_pk_mul_f32 v[150:151], v[140:141], v[28:29] op_sel_hi:[0,1]
	v_pk_mul_f32 v[152:153], v[140:141], v[30:31] op_sel_hi:[0,1]
	v_cvt_pk_bf16_f32 v150, v150, v151
	v_cvt_pk_bf16_f32 v151, v152, v153
	v_cvt_pk_bf16_f32 v152, v158, v159
	v_cvt_pk_bf16_f32 v153, v156, v157
	global_store_dwordx4 v149, v[150:153], s[98:99] offset:256
	s_add_u32 s98, s98, 0x14000
	s_addc_u32 s99, s99, 0
	v_pk_mul_f32 v[156:157], v[140:141], v[50:51] op_sel_hi:[0,1]
	v_pk_mul_f32 v[158:159], v[140:141], v[48:49] op_sel_hi:[0,1]
	v_pk_mul_f32 v[150:151], v[140:141], v[52:53] op_sel_hi:[0,1]
	v_pk_mul_f32 v[152:153], v[140:141], v[54:55] op_sel_hi:[0,1]
	v_cvt_pk_bf16_f32 v150, v150, v151
	v_cvt_pk_bf16_f32 v151, v152, v153
	v_cvt_pk_bf16_f32 v152, v158, v159
	v_cvt_pk_bf16_f32 v153, v156, v157
	global_store_dwordx4 v149, v[150:153], s[98:99]
	v_pk_mul_f32 v[156:157], v[140:141], v[18:19] op_sel_hi:[0,1]
	v_pk_mul_f32 v[158:159], v[140:141], v[16:17] op_sel_hi:[0,1]
	v_pk_mul_f32 v[150:151], v[140:141], v[20:21] op_sel_hi:[0,1]
	v_pk_mul_f32 v[152:153], v[140:141], v[22:23] op_sel_hi:[0,1]
	v_cvt_pk_bf16_f32 v150, v150, v151
	v_cvt_pk_bf16_f32 v151, v152, v153
	v_cvt_pk_bf16_f32 v152, v158, v159
	v_cvt_pk_bf16_f32 v153, v156, v157
	global_store_dwordx4 v149, v[150:153], s[98:99] offset:256
	s_add_u32 s98, s98, 0x14000
	s_addc_u32 s99, s99, 0
	v_pk_mul_f32 v[156:157], v[140:141], v[42:43] op_sel_hi:[0,1]
	v_pk_mul_f32 v[158:159], v[140:141], v[40:41] op_sel_hi:[0,1]
	v_pk_mul_f32 v[150:151], v[140:141], v[44:45] op_sel_hi:[0,1]
	v_pk_mul_f32 v[152:153], v[140:141], v[46:47] op_sel_hi:[0,1]
	v_cvt_pk_bf16_f32 v150, v150, v151
	v_cvt_pk_bf16_f32 v151, v152, v153
	v_cvt_pk_bf16_f32 v152, v158, v159
	v_cvt_pk_bf16_f32 v153, v156, v157
	global_store_dwordx4 v149, v[150:153], s[98:99]
	s_nop 1
	v_pk_mul_f32 v[150:151], v[140:141], v[12:13] op_sel_hi:[0,1]
	v_pk_mul_f32 v[152:153], v[140:141], v[14:15] op_sel_hi:[0,1]
	v_cvt_pk_bf16_f32 v150, v150, v151
	v_cvt_pk_bf16_f32 v151, v152, v153
	v_pk_mul_f32 v[156:157], v[140:141], v[10:11] op_sel_hi:[0,1]
	v_pk_mul_f32 v[158:159], v[140:141], v[8:9] op_sel_hi:[0,1]
	v_cvt_pk_bf16_f32 v152, v158, v159
	v_cvt_pk_bf16_f32 v153, v156, v157
	global_store_dwordx4 v149, v[150:153], s[98:99] offset:256
	s_add_u32 s98, s98, 0x14000
	s_addc_u32 s99, s99, 0
	v_pk_mul_f32 v[154:155], v[140:141], v[32:33] op_sel_hi:[0,1]
	s_and_b32 s36, s70, -2
	v_pk_mul_f32 v[144:145], v[140:141], v[38:39] op_sel_hi:[0,1]
	v_pk_mul_f32 v[142:143], v[140:141], v[36:37] op_sel_hi:[0,1]
	v_pk_mul_f32 v[152:153], v[140:141], v[34:35] op_sel_hi:[0,1]
	v_cvt_pk_bf16_f32 v142, v142, v143
	v_cvt_pk_bf16_f32 v143, v144, v145
	v_cvt_pk_bf16_f32 v144, v154, v155
	v_cvt_pk_bf16_f32 v145, v152, v153
	global_store_dwordx4 v149, v[142:145], s[98:99]
	s_cmp_lg_u32 s36, 2
	s_movk_i32 s84, 0x3000
	v_pk_mul_f32 v[144:145], v[140:141], v[6:7] op_sel_hi:[0,1]
	v_pk_mul_f32 v[142:143], v[140:141], v[4:5] op_sel_hi:[0,1]
	s_mov_b32 s92, 0x358637bd
	v_pk_mul_f32 v[152:153], v[140:141], v[2:3] op_sel_hi:[0,1]
	v_pk_mul_f32 v[154:155], v[140:141], v[0:1] op_sel_hi:[0,1]
	v_cvt_pk_bf16_f32 v142, v142, v143
	v_cvt_pk_bf16_f32 v143, v144, v145
	v_cvt_pk_bf16_f32 v144, v154, v155
	v_cvt_pk_bf16_f32 v145, v152, v153
	global_store_dwordx4 v149, v[142:145], s[98:99] offset:256
	s_cbranch_scc1 .LBB0_189
;     __device__ __forceinline__ void operator()(const f32x4 (&acc)[2][2][4][2], const Unit& u, int wr, int wc, int fr, int fq) const {
;     ...
;         if (u.pn == 2 || u.pn == 3) {
; #pragma unroll
;             for (int ai = 0; ai < 2; ++ai)
; #pragma unroll
;                 for (int bj = 0; bj < 2; ++bj) { float mx = 0.f;
; #pragma unroll
;                     for (int m = 0; m < 4; ++m) { const f32x4 a = acc[ai][bj][m][0], b = acc[ai][bj][m][1];
;                         float ss = (a[0] * a[0] + a[1] * a[1]) + (a[2] * a[2] + a[3] * a[3]) + (b[0] * b[0] + b[1] * b[1]) + (b[2] * b[2] + b[3] * b[3]);
;                         ss += __shfl_xor(ss, 16); ss += __shfl_xor(ss, 32); mx = fmaxf(mx, ss); }
;                     mx = fmaxf(mx, __shfl_xor(mx, 1)); mx = fmaxf(mx, __shfl_xor(mx, 2)); mx = fmaxf(mx, __shfl_xor(mx, 4)); mx = fmaxf(mx, __shfl_xor(mx, 8));
;                     if (fr == 0 && fq == 0) { const int b = u.pm >> 4, tile = (u.pm * 4 + ai * 2 + wr) & 63, head = (u.pn - 2) * 4 + bj * 2 + (wc >> 1), half = wc & 1;
;                         atomicMax(kn2 + ((b * 8 + head) * 2 + half) * 64 + tile, __float_as_uint(mx)); } }
.Lg1_join:
	v_mul_f32_e32 v125, v125, v125
	v_mul_f32_e32 v117, v117, v117
	v_fmac_f32_e32 v125, v124, v124
	v_mul_f32_e32 v124, v127, v127
	v_fmac_f32_e32 v117, v116, v116
	v_mul_f32_e32 v116, v119, v119
	v_mul_f32_e32 v109, v109, v109
	v_mul_f32_e32 v101, v101, v101
	v_fmac_f32_e32 v124, v126, v126
	v_mul_f32_e32 v121, v121, v121
	v_fmac_f32_e32 v116, v118, v118
	v_mul_f32_e32 v113, v113, v113
	v_fmac_f32_e32 v109, v108, v108
	v_mul_f32_e32 v108, v111, v111
	v_fmac_f32_e32 v101, v100, v100
	v_mul_f32_e32 v100, v103, v103
	v_add_f32_e32 v124, v125, v124
	v_fmac_f32_e32 v121, v120, v120
	v_add_f32_e32 v116, v117, v116
	v_fmac_f32_e32 v113, v112, v112
	v_fmac_f32_e32 v108, v110, v110
	v_mul_f32_e32 v105, v105, v105
	v_fmac_f32_e32 v100, v102, v102
	v_mul_f32_e32 v97, v97, v97
	v_cmp_lt_i32_e32 vcc, v218, v220
	v_add_f32_e32 v120, v124, v121
	v_mul_f32_e32 v121, v123, v123
	v_add_f32_e32 v112, v116, v113
	v_mul_f32_e32 v113, v115, v115
	v_add_f32_e32 v108, v109, v108
	v_fmac_f32_e32 v105, v104, v104
	v_add_f32_e32 v100, v101, v100
	v_fmac_f32_e32 v97, v96, v96
	v_cndmask_b32_e32 v140, v213, v218, vcc
	v_fmac_f32_e32 v121, v122, v122
	v_fmac_f32_e32 v113, v114, v114
	v_add_f32_e32 v104, v108, v105
	v_mul_f32_e32 v105, v107, v107
	v_add_f32_e32 v96, v100, v97
	v_mul_f32_e32 v97, v99, v99
	v_lshlrev_b32_e32 v140, 2, v140
	v_add_f32_e32 v122, v121, v120
	v_add_f32_e32 v112, v113, v112
	v_fmac_f32_e32 v105, v106, v106
	v_fmac_f32_e32 v97, v98, v98
	ds_bpermute_b32 v123, v140, v122
	ds_bpermute_b32 v113, v140, v112
	v_add_f32_e32 v104, v105, v104
	v_add_f32_e32 v96, v97, v96
	ds_bpermute_b32 v105, v140, v104
	ds_bpermute_b32 v97, v140, v96
	v_cmp_lt_i32_e32 vcc, v219, v220
	s_waitcnt lgkmcnt(0)
	v_add_f32_e32 v122, v122, v123
	v_add_f32_e32 v98, v112, v113
	v_cndmask_b32_e32 v142, v213, v219, vcc
	v_lshlrev_b32_e32 v121, 2, v142
	ds_bpermute_b32 v123, v121, v122
	ds_bpermute_b32 v99, v121, v98
	v_add_f32_e32 v100, v104, v105
	v_add_f32_e32 v96, v96, v97
	ds_bpermute_b32 v101, v121, v100
	ds_bpermute_b32 v97, v121, v96
	v_cmp_lt_i32_e32 vcc, v252, v220
	s_waitcnt lgkmcnt(0)
	v_add_f32_e32 v102, v122, v123
	v_add_f32_e32 v98, v98, v99
	v_cndmask_b32_e32 v120, v213, v252, vcc
	v_max3_f32 v98, v102, 0, v98
	v_add_f32_e32 v99, v100, v101
	v_add_f32_e32 v96, v96, v97
	v_lshlrev_b32_e32 v120, 2, v120
	v_max3_f32 v97, v98, v99, v96
	ds_bpermute_b32 v98, v120, v97
	v_cmp_lt_i32_e32 vcc, v227, v220
	s_waitcnt lgkmcnt(0)
	v_max_f32_e32 v98, v98, v98
	v_cndmask_b32_e32 v96, v213, v227, vcc
	v_lshlrev_b32_e32 v96, 2, v96
	v_max_f32_e32 v98, v97, v98
	ds_bpermute_b32 v99, v96, v98
	v_cmp_lt_i32_e32 vcc, v216, v220
	s_waitcnt lgkmcnt(0)
	v_max_f32_e32 v99, v99, v99
	v_cndmask_b32_e32 v97, v213, v216, vcc
	v_lshlrev_b32_e32 v97, 2, v97
	v_max_f32_e32 v99, v98, v99
	ds_bpermute_b32 v100, v97, v99
	v_cmp_lt_i32_e32 vcc, v217, v220
	s_waitcnt lgkmcnt(0)
	v_max_f32_e32 v100, v100, v100
	v_cndmask_b32_e32 v98, v213, v217, vcc
	v_lshlrev_b32_e32 v98, 2, v98
	v_max_f32_e32 v99, v99, v100
	ds_bpermute_b32 v100, v98, v99
	s_and_saveexec_b64 s[36:37], s[38:39]
	s_cbranch_execz .LBB0_173
	s_waitcnt lgkmcnt(0)
	v_max_f32_e32 v100, v100, v100
	v_max_f32_e32 v99, v99, v99
	s_mov_b64 s[58:59], exec
	v_max_f32_e32 v99, v99, v100
	s_mov_b32 s51, 0
